# GQA tile body software-pipelined by hand + NA rpb bias gathered from an LDS copy (parallel ds_read2) instead of 64 serialized global loads per tile
# speedup vs baseline: 1.0252x; 1.0252x over previous
; template <int DQ, bool NA, int NQG>
; DI void attn_wg(const half_t* Qp, const half_t* Kp, const half_t* Vp, int q0, bool active, int seg0_start, int seg0_tiles,
;                 int seg1_start, int seg1_tiles, const float* rpb_h, int rq, char* smem, int tid, f16v (&O)[2][NQG]) {
;     ...
;       for (int st = 0; st < 2; ++st) {
;         f16v S[NQG];
; #pragma unroll
;         for (int qg = 0; qg < NQG; ++qg)
; #pragma unroll
;           for (int i = 0; i < 16; ++i) S[qg][i] = 0.f;
; #pragma unroll
;         for (int ks = 0; ks < NKS; ++ks) {
;           const h8 kf = *(const h8*)(ksm + (st * 32) * KSTR + ks * 16);
; #pragma unroll
;           for (int qg = 0; qg < NQG; ++qg) S[qg] = __builtin_amdgcn_mfma_f32_32x32x16_f16(kf, qf[qg][ks], S[qg], 0, 0, 0);
;         }
;         if (masked) {
;           const int cb = st * 32;
;           const int dr = krow - rq + 7;
; #pragma unroll
;           for (int qg = 0; qg < NQG; ++qg) {
;             const int qc = qg * 32 + r;
;             const int cs = min(max(qc - 8, 0), 48);
; #pragma unroll
;             for (int i = 0; i < 16; ++i) {
;               const int c = cb + (i & 3) + 8 * (i >> 2) + 4 * h;
;               const bool valid = (c >= cs) && (c < cs + 16);
;               float bias = 0.f;
;               if (valid) bias = rpb_h[dr * 31 + (c - qc + 15)] * LOG2E;
;               S[qg][i] = valid ? S[qg][i] + bias : -1e30f;
;             }
;           }
;         }
;         h4 vf[2][2][2];
; #pragma unroll
;         for (int dvt = 0; dvt < 2; ++dvt)
; #pragma unroll
;           for (int sx = 0; sx < 2; ++sx)
; #pragma unroll
;             for (int hf = 0; hf < 2; ++hf) vf[dvt][sx][hf] = *(const h4*)(vsm + (dvt * 32) * VSTR + st * 32 + sx * 16 + hf * 8);
; #pragma unroll
;         for (int qg = 0; qg < NQG; ++qg) {
;           h8 P[2];
;           float mx = S[qg][0];
; #pragma unroll
;           for (int i = 1; i < 16; ++i) mx = fmaxf(mx, S[qg][i]);
;           mx = fmaxf(mx, __shfl_xor(mx, 32));
;           if (__builtin_amdgcn_ballot_w64(mx > mrun[qg] + 8.f) != 0ull) {
;             const float mnew = fmaxf(mrun[qg], mx);
;             const float alpha = __builtin_amdgcn_exp2f(mrun[qg] - mnew);
;             lrun[qg] *= alpha;
; #pragma unroll
;             for (int dvt = 0; dvt < 2; ++dvt)
; #pragma unroll
;               for (int i = 0; i < 16; ++i) O[dvt][qg][i] *= alpha;
;             mrun[qg] = mnew;
.LBB0_1917:
	v_cndmask_b32_e64 v66, 0, 1, s[14:15]
	v_cmp_ne_u32_e64 s[6:7], 1, v66
	s_andn2_b64 vcc, exec, s[14:15]
	s_cbranch_vccnz .LBB0_1924
	s_bitcmp1_b32 s22, 0
	s_cselect_b32 s22, 0x5800, 0
	v_add3_u32 v187, s22, v237, v156
	v_add3_u32 v189, s22, v237, v155
	v_add_u32_e32 v197, 0x4600, v189
	v_add_u32_e32 v189, 0x3400, v189
	ds_read_b128 v[198:201], v187 offset:0
	ds_read_b128 v[202:205], v187 offset:32
	ds_read_b128 v[206:209], v187 offset:64
	ds_read_b128 v[210:213], v187 offset:96
	ds_read2_b64 v[138:141], v189 offset0:0 offset1:2
	ds_read2_b64 v[142:145], v189 offset0:4 offset1:6
	ds_read2_b64 v[146:149], v197 offset0:0 offset1:2
	ds_read2_b64 v[150:153], v197 offset0:4 offset1:6
	s_waitcnt lgkmcnt(7)
	v_mfma_f32_32x32x16_f16 v[82:97], v[198:201], v[98:101], 0
	s_waitcnt lgkmcnt(6)
	v_mfma_f32_32x32x16_f16 v[82:97], v[202:205], v[102:105], v[82:97]
	s_waitcnt lgkmcnt(5)
	v_mfma_f32_32x32x16_f16 v[82:97], v[206:209], v[106:109], v[82:97]
	s_waitcnt lgkmcnt(4)
	v_mfma_f32_32x32x16_f16 v[82:97], v[210:213], v[110:113], v[82:97]
	s_nop 11
	v_max3_f32 v232, v82, v83, v84
	v_max3_f32 v233, v85, v86, v87
	v_max3_f32 v232, v232, v88, v89
	v_max3_f32 v233, v233, v90, v91
	v_max3_f32 v232, v232, v92, v93
	v_max3_f32 v233, v233, v94, v95
	v_max3_f32 v232, v232, v96, v97
	v_mfma_f32_32x32x16_f16 v[66:81], v[198:201], v[114:117], 0
	v_max_f32_e32 v232, v232, v233
	v_mov_b32_e32 v233, v232
	s_nop 1
	v_permlane32_swap_b32_e32 v233, v232
	v_max_f32_e32 v232, v232, v233
	v_add_f32_e32 v233, 0x41000000, v194
	v_cmp_gt_f32_e32 vcc, v232, v233
	s_cbranch_vccnz .Lresc_gqa_0
.Lcont_gqa_0:
	v_pk_add_f32 v[82:83], v[82:83], v[194:195] op_sel_hi:[1,0] neg_lo:[0,1] neg_hi:[0,1]
	v_pk_add_f32 v[84:85], v[84:85], v[194:195] op_sel_hi:[1,0] neg_lo:[0,1] neg_hi:[0,1]
	v_exp_f32_e32 v82, v82
	v_mfma_f32_32x32x16_f16 v[66:81], v[202:205], v[118:121], v[66:81]
	v_exp_f32_e32 v83, v83
	v_pk_add_f32 v[86:87], v[86:87], v[194:195] op_sel_hi:[1,0] neg_lo:[0,1] neg_hi:[0,1]
	v_exp_f32_e32 v84, v84
	v_exp_f32_e32 v85, v85
	v_pk_add_f32 v[88:89], v[88:89], v[194:195] op_sel_hi:[1,0] neg_lo:[0,1] neg_hi:[0,1]
	v_exp_f32_e32 v86, v86
	v_exp_f32_e32 v87, v87
	v_pk_add_f32 v[90:91], v[90:91], v[194:195] op_sel_hi:[1,0] neg_lo:[0,1] neg_hi:[0,1]
	v_exp_f32_e32 v88, v88
	v_exp_f32_e32 v89, v89
	v_mfma_f32_32x32x16_f16 v[66:81], v[206:209], v[122:125], v[66:81]
	v_pk_add_f32 v[92:93], v[92:93], v[194:195] op_sel_hi:[1,0] neg_lo:[0,1] neg_hi:[0,1]
	v_exp_f32_e32 v90, v90
	v_exp_f32_e32 v91, v91
	v_pk_add_f32 v[94:95], v[94:95], v[194:195] op_sel_hi:[1,0] neg_lo:[0,1] neg_hi:[0,1]
	v_exp_f32_e32 v92, v92
	v_exp_f32_e32 v93, v93
	v_pk_add_f32 v[96:97], v[96:97], v[194:195] op_sel_hi:[1,0] neg_lo:[0,1] neg_hi:[0,1]
	v_exp_f32_e32 v94, v94
	v_exp_f32_e32 v95, v95
	v_exp_f32_e32 v96, v96
	v_mfma_f32_32x32x16_f16 v[66:81], v[210:213], v[126:129], v[66:81]
	v_exp_f32_e32 v97, v97
	v_cvt_pk_f16_f32 v214, v82, v83
	v_cvt_pk_f16_f32 v215, v84, v85
	v_cvt_pk_f16_f32 v216, v86, v87
	v_cvt_pk_f16_f32 v217, v88, v89
	v_cvt_pk_f16_f32 v218, v90, v91
	v_cvt_pk_f16_f32 v219, v92, v93
	v_cvt_pk_f16_f32 v220, v94, v95
	v_cvt_pk_f16_f32 v221, v96, v97
	v_pk_add_f32 v[222:223], v[82:83], v[84:85]
	v_pk_add_f32 v[224:225], v[86:87], v[88:89]
	v_pk_add_f32 v[226:227], v[90:91], v[92:93]
	v_pk_add_f32 v[228:229], v[94:95], v[96:97]
	v_pk_add_f32 v[222:223], v[222:223], v[224:225]
	v_pk_add_f32 v[226:227], v[226:227], v[228:229]
	v_pk_add_f32 v[222:223], v[222:223], v[226:227]
	v_add_f32_e32 v222, v222, v223
	v_add_f32_e32 v183, v183, v222
	ds_read_b128 v[198:201], v187 offset:4608
	ds_read_b128 v[202:205], v187 offset:4640
	ds_read_b128 v[206:209], v187 offset:4672
	ds_read_b128 v[210:213], v187 offset:4704
	v_max3_f32 v232, v66, v67, v68
	v_max3_f32 v233, v69, v70, v71
	v_max3_f32 v232, v232, v72, v73
	v_max3_f32 v233, v233, v74, v75
	s_waitcnt lgkmcnt(7)
	v_mfma_f32_32x32x16_f16 v[2:17], v[138:141], v[214:217], v[2:17]
	v_max3_f32 v232, v232, v76, v77
	v_max3_f32 v233, v233, v78, v79
	v_max3_f32 v232, v232, v80, v81
	v_max_f32_e32 v232, v232, v233
	v_mov_b32_e32 v233, v232
	s_nop 1
	v_permlane32_swap_b32_e32 v233, v232
	v_max_f32_e32 v232, v232, v233
	s_waitcnt lgkmcnt(5)
	v_mfma_f32_32x32x16_f16 v[18:33], v[146:149], v[214:217], v[18:33]
	v_add_f32_e32 v233, 0x41000000, v196
	v_cmp_gt_f32_e32 vcc, v232, v233
	s_cbranch_vccnz .Lresc_gqa_1
; template <int DQ, bool NA, int NQG>
; DI void attn_wg(const half_t* Qp, const half_t* Kp, const half_t* Vp, int q0, bool active, int seg0_start, int seg0_tiles,
;                 int seg1_start, int seg1_tiles, const float* rpb_h, int rq, char* smem, int tid, f16v (&O)[2][NQG]) {
;     ...
;         for (int qg = 0; qg < NQG; ++qg) {
;           h8 P[2];
;           float mx = S[qg][0];
; #pragma unroll
;           for (int i = 1; i < 16; ++i) mx = fmaxf(mx, S[qg][i]);
;           mx = fmaxf(mx, __shfl_xor(mx, 32));
;           if (__builtin_amdgcn_ballot_w64(mx > mrun[qg] + 8.f) != 0ull) {
;             const float mnew = fmaxf(mrun[qg], mx);
;             const float alpha = __builtin_amdgcn_exp2f(mrun[qg] - mnew);
;             lrun[qg] *= alpha;
; #pragma unroll
;             for (int dvt = 0; dvt < 2; ++dvt)
; #pragma unroll
;               for (int i = 0; i < 16; ++i) O[dvt][qg][i] *= alpha;
;             mrun[qg] = mnew;
;           }
;           const float mn = mrun[qg];
;           f2 rs2 = {0.f, 0.f};
;           const f2 mn2 = {mn, mn};
; #pragma unroll
;           for (int i = 0; i < 16; i += 2) {
;             const f2 s2 = {S[qg][i], S[qg][i + 1]};
;             const f2 d2 = s2 - mn2;
;             f2 p2;
;             p2.x = __builtin_amdgcn_exp2f(d2.x);
;             p2.y = __builtin_amdgcn_exp2f(d2.y);
;             if (NA) { p2.x = (s2.x <= -1e29f) ? 0.f : p2.x; p2.y = (s2.y <= -1e29f) ? 0.f : p2.y; }
;             rs2 += p2;
;             P[i >> 3][i & 7] = (half_t)p2.x;
;             P[i >> 3][(i & 7) + 1] = (half_t)p2.y;
;           }
;           lrun[qg] += rs2.x + rs2.y;
; #pragma unroll
;           for (int dvt = 0; dvt < 2; ++dvt) {
; #pragma unroll
;             for (int sx = 0; sx < 2; ++sx) {
;               const h8 va = __builtin_shufflevector(vf[dvt][sx][0], vf[dvt][sx][1], 0, 1, 2, 3, 4, 5, 6, 7);
;               O[dvt][qg] = __builtin_amdgcn_mfma_f32_32x32x16_f16(va, P[sx], O[dvt][qg], 0, 0, 0);
;             }
;           }
;         }
.Lcont_gqa_1:
	v_pk_add_f32 v[66:67], v[66:67], v[196:197] op_sel_hi:[1,0] neg_lo:[0,1] neg_hi:[0,1]
	v_pk_add_f32 v[68:69], v[68:69], v[196:197] op_sel_hi:[1,0] neg_lo:[0,1] neg_hi:[0,1]
	v_exp_f32_e32 v66, v66
	v_exp_f32_e32 v67, v67
	v_pk_add_f32 v[70:71], v[70:71], v[196:197] op_sel_hi:[1,0] neg_lo:[0,1] neg_hi:[0,1]
	v_mfma_f32_32x32x16_f16 v[2:17], v[142:145], v[218:221], v[2:17]
	v_exp_f32_e32 v68, v68
	v_exp_f32_e32 v69, v69
	v_pk_add_f32 v[72:73], v[72:73], v[196:197] op_sel_hi:[1,0] neg_lo:[0,1] neg_hi:[0,1]
	v_exp_f32_e32 v70, v70
	v_exp_f32_e32 v71, v71
	v_pk_add_f32 v[74:75], v[74:75], v[196:197] op_sel_hi:[1,0] neg_lo:[0,1] neg_hi:[0,1]
	v_exp_f32_e32 v72, v72
	s_waitcnt lgkmcnt(4)
	v_mfma_f32_32x32x16_f16 v[18:33], v[150:153], v[218:221], v[18:33]
	v_exp_f32_e32 v73, v73
	v_pk_add_f32 v[76:77], v[76:77], v[196:197] op_sel_hi:[1,0] neg_lo:[0,1] neg_hi:[0,1]
	v_exp_f32_e32 v74, v74
	v_exp_f32_e32 v75, v75
	v_pk_add_f32 v[78:79], v[78:79], v[196:197] op_sel_hi:[1,0] neg_lo:[0,1] neg_hi:[0,1]
	s_waitcnt lgkmcnt(3)
	v_mfma_f32_32x32x16_f16 v[82:97], v[198:201], v[98:101], 0
	v_exp_f32_e32 v76, v76
	v_exp_f32_e32 v77, v77
	v_pk_add_f32 v[80:81], v[80:81], v[196:197] op_sel_hi:[1,0] neg_lo:[0,1] neg_hi:[0,1]
	s_waitcnt lgkmcnt(2)
	v_mfma_f32_32x32x16_f16 v[82:97], v[202:205], v[102:105], v[82:97]
	v_exp_f32_e32 v78, v78
	v_exp_f32_e32 v79, v79
	v_exp_f32_e32 v80, v80
	s_waitcnt lgkmcnt(1)
	v_mfma_f32_32x32x16_f16 v[82:97], v[206:209], v[106:109], v[82:97]
	v_exp_f32_e32 v81, v81
	v_cvt_pk_f16_f32 v214, v66, v67
	v_cvt_pk_f16_f32 v215, v68, v69
	s_waitcnt lgkmcnt(0)
	v_mfma_f32_32x32x16_f16 v[82:97], v[210:213], v[110:113], v[82:97]
	v_cvt_pk_f16_f32 v216, v70, v71
	v_cvt_pk_f16_f32 v217, v72, v73
	v_cvt_pk_f16_f32 v218, v74, v75
	v_cvt_pk_f16_f32 v219, v76, v77
	v_cvt_pk_f16_f32 v220, v78, v79
	v_cvt_pk_f16_f32 v221, v80, v81
	v_pk_add_f32 v[222:223], v[66:67], v[68:69]
	v_pk_add_f32 v[224:225], v[70:71], v[72:73]
	v_pk_add_f32 v[226:227], v[74:75], v[76:77]
	v_pk_add_f32 v[228:229], v[78:79], v[80:81]
	v_pk_add_f32 v[222:223], v[222:223], v[224:225]
	v_pk_add_f32 v[226:227], v[226:227], v[228:229]
	v_pk_add_f32 v[222:223], v[222:223], v[226:227]
	v_add_f32_e32 v222, v222, v223
	v_add_f32_e32 v1, v1, v222
	v_max3_f32 v232, v82, v83, v84
	v_max3_f32 v233, v85, v86, v87
	v_max3_f32 v232, v232, v88, v89
	v_max3_f32 v233, v233, v90, v91
	v_mfma_f32_32x32x16_f16 v[34:49], v[138:141], v[214:217], v[34:49]
	v_max3_f32 v232, v232, v92, v93
	v_max3_f32 v233, v233, v94, v95
	v_max3_f32 v232, v232, v96, v97
	v_max_f32_e32 v232, v232, v233
	v_mov_b32_e32 v233, v232
	s_nop 1
	v_permlane32_swap_b32_e32 v233, v232
	v_max_f32_e32 v232, v232, v233
	v_mfma_f32_32x32x16_f16 v[50:65], v[146:149], v[214:217], v[50:65]
	v_add_f32_e32 v233, 0x41000000, v194
	v_cmp_gt_f32_e32 vcc, v232, v233
	s_cbranch_vccnz .Lresc_gqa_2
.Lcont_gqa_2:
	v_pk_add_f32 v[82:83], v[82:83], v[194:195] op_sel_hi:[1,0] neg_lo:[0,1] neg_hi:[0,1]
	v_pk_add_f32 v[84:85], v[84:85], v[194:195] op_sel_hi:[1,0] neg_lo:[0,1] neg_hi:[0,1]
	v_exp_f32_e32 v82, v82
	v_exp_f32_e32 v83, v83
	v_pk_add_f32 v[86:87], v[86:87], v[194:195] op_sel_hi:[1,0] neg_lo:[0,1] neg_hi:[0,1]
	v_mfma_f32_32x32x16_f16 v[34:49], v[142:145], v[218:221], v[34:49]
	v_exp_f32_e32 v84, v84
	v_exp_f32_e32 v85, v85
	v_pk_add_f32 v[88:89], v[88:89], v[194:195] op_sel_hi:[1,0] neg_lo:[0,1] neg_hi:[0,1]
	v_exp_f32_e32 v86, v86
	v_exp_f32_e32 v87, v87
	v_pk_add_f32 v[90:91], v[90:91], v[194:195] op_sel_hi:[1,0] neg_lo:[0,1] neg_hi:[0,1]
	v_exp_f32_e32 v88, v88
	v_mfma_f32_32x32x16_f16 v[50:65], v[150:153], v[218:221], v[50:65]
	ds_read2_b64 v[138:141], v189 offset0:8 offset1:10
	ds_read2_b64 v[142:145], v189 offset0:12 offset1:14
	ds_read2_b64 v[146:149], v197 offset0:8 offset1:10
	ds_read2_b64 v[150:153], v197 offset0:12 offset1:14
	v_exp_f32_e32 v89, v89
	v_pk_add_f32 v[92:93], v[92:93], v[194:195] op_sel_hi:[1,0] neg_lo:[0,1] neg_hi:[0,1]
	v_exp_f32_e32 v90, v90
	v_exp_f32_e32 v91, v91
	v_pk_add_f32 v[94:95], v[94:95], v[194:195] op_sel_hi:[1,0] neg_lo:[0,1] neg_hi:[0,1]
	v_mfma_f32_32x32x16_f16 v[66:81], v[198:201], v[114:117], 0
	v_exp_f32_e32 v92, v92
	v_exp_f32_e32 v93, v93
	v_pk_add_f32 v[96:97], v[96:97], v[194:195] op_sel_hi:[1,0] neg_lo:[0,1] neg_hi:[0,1]
	v_mfma_f32_32x32x16_f16 v[66:81], v[202:205], v[118:121], v[66:81]
	v_exp_f32_e32 v94, v94
	v_exp_f32_e32 v95, v95
	v_exp_f32_e32 v96, v96
	v_mfma_f32_32x32x16_f16 v[66:81], v[206:209], v[122:125], v[66:81]
	v_exp_f32_e32 v97, v97
	v_cvt_pk_f16_f32 v214, v82, v83
	v_cvt_pk_f16_f32 v215, v84, v85
	v_mfma_f32_32x32x16_f16 v[66:81], v[210:213], v[126:129], v[66:81]
	v_cvt_pk_f16_f32 v216, v86, v87
	v_cvt_pk_f16_f32 v217, v88, v89
	v_cvt_pk_f16_f32 v218, v90, v91
	v_cvt_pk_f16_f32 v219, v92, v93
	v_cvt_pk_f16_f32 v220, v94, v95
	v_cvt_pk_f16_f32 v221, v96, v97
	v_pk_add_f32 v[222:223], v[82:83], v[84:85]
	v_pk_add_f32 v[224:225], v[86:87], v[88:89]
	v_pk_add_f32 v[226:227], v[90:91], v[92:93]
	v_pk_add_f32 v[228:229], v[94:95], v[96:97]
	v_pk_add_f32 v[222:223], v[222:223], v[224:225]
	v_pk_add_f32 v[226:227], v[226:227], v[228:229]
	v_pk_add_f32 v[222:223], v[222:223], v[226:227]
	v_add_f32_e32 v222, v222, v223
	v_add_f32_e32 v183, v183, v222
	v_max3_f32 v232, v66, v67, v68
	v_max3_f32 v233, v69, v70, v71
	v_max3_f32 v232, v232, v72, v73
	v_max3_f32 v233, v233, v74, v75
	s_waitcnt lgkmcnt(3)
	v_mfma_f32_32x32x16_f16 v[2:17], v[138:141], v[214:217], v[2:17]
	v_max3_f32 v232, v232, v76, v77
	v_max3_f32 v233, v233, v78, v79
	v_max3_f32 v232, v232, v80, v81
	v_max_f32_e32 v232, v232, v233
	v_mov_b32_e32 v233, v232
	s_nop 1
	v_permlane32_swap_b32_e32 v233, v232
	v_max_f32_e32 v232, v232, v233
	s_waitcnt lgkmcnt(1)
	v_mfma_f32_32x32x16_f16 v[18:33], v[146:149], v[214:217], v[18:33]
	v_add_f32_e32 v233, 0x41000000, v196
	v_cmp_gt_f32_e32 vcc, v232, v233
	s_cbranch_vccnz .Lresc_gqa_3
; template <int DQ, bool NA, int NQG>
; DI void attn_wg(const half_t* Qp, const half_t* Kp, const half_t* Vp, int q0, bool active, int seg0_start, int seg0_tiles,
;                 int seg1_start, int seg1_tiles, const float* rpb_h, int rq, char* smem, int tid, f16v (&O)[2][NQG]) {
;     ...
;           if (__builtin_amdgcn_ballot_w64(mx > mrun[qg] + 8.f) != 0ull) {
;             const float mnew = fmaxf(mrun[qg], mx);
;             const float alpha = __builtin_amdgcn_exp2f(mrun[qg] - mnew);
;             lrun[qg] *= alpha;
; #pragma unroll
;             for (int dvt = 0; dvt < 2; ++dvt)
; #pragma unroll
;               for (int i = 0; i < 16; ++i) O[dvt][qg][i] *= alpha;
;             mrun[qg] = mnew;
;           }
;           const float mn = mrun[qg];
;           f2 rs2 = {0.f, 0.f};
;           const f2 mn2 = {mn, mn};
; #pragma unroll
;           for (int i = 0; i < 16; i += 2) {
;             const f2 s2 = {S[qg][i], S[qg][i + 1]};
;             const f2 d2 = s2 - mn2;
;             f2 p2;
;             p2.x = __builtin_amdgcn_exp2f(d2.x);
;             p2.y = __builtin_amdgcn_exp2f(d2.y);
;             if (NA) { p2.x = (s2.x <= -1e29f) ? 0.f : p2.x; p2.y = (s2.y <= -1e29f) ? 0.f : p2.y; }
;             rs2 += p2;
;             P[i >> 3][i & 7] = (half_t)p2.x;
;             P[i >> 3][(i & 7) + 1] = (half_t)p2.y;
;           }
;           lrun[qg] += rs2.x + rs2.y;
; #pragma unroll
;           for (int dvt = 0; dvt < 2; ++dvt) {
; #pragma unroll
;             for (int sx = 0; sx < 2; ++sx) {
;               const h8 va = __builtin_shufflevector(vf[dvt][sx][0], vf[dvt][sx][1], 0, 1, 2, 3, 4, 5, 6, 7);
;               O[dvt][qg] = __builtin_amdgcn_mfma_f32_32x32x16_f16(va, P[sx], O[dvt][qg], 0, 0, 0);
;             }
;           }
;         }
.Lcont_gqa_3:
	v_pk_add_f32 v[66:67], v[66:67], v[196:197] op_sel_hi:[1,0] neg_lo:[0,1] neg_hi:[0,1]
	v_pk_add_f32 v[68:69], v[68:69], v[196:197] op_sel_hi:[1,0] neg_lo:[0,1] neg_hi:[0,1]
	v_exp_f32_e32 v66, v66
	v_exp_f32_e32 v67, v67
	v_pk_add_f32 v[70:71], v[70:71], v[196:197] op_sel_hi:[1,0] neg_lo:[0,1] neg_hi:[0,1]
	v_mfma_f32_32x32x16_f16 v[2:17], v[142:145], v[218:221], v[2:17]
	v_exp_f32_e32 v68, v68
	v_exp_f32_e32 v69, v69
	v_pk_add_f32 v[72:73], v[72:73], v[196:197] op_sel_hi:[1,0] neg_lo:[0,1] neg_hi:[0,1]
	v_exp_f32_e32 v70, v70
	v_exp_f32_e32 v71, v71
	v_pk_add_f32 v[74:75], v[74:75], v[196:197] op_sel_hi:[1,0] neg_lo:[0,1] neg_hi:[0,1]
	v_exp_f32_e32 v72, v72
	s_waitcnt lgkmcnt(0)
	v_mfma_f32_32x32x16_f16 v[18:33], v[150:153], v[218:221], v[18:33]
	v_exp_f32_e32 v73, v73
	v_pk_add_f32 v[76:77], v[76:77], v[196:197] op_sel_hi:[1,0] neg_lo:[0,1] neg_hi:[0,1]
	v_exp_f32_e32 v74, v74
	v_exp_f32_e32 v75, v75
	v_pk_add_f32 v[78:79], v[78:79], v[196:197] op_sel_hi:[1,0] neg_lo:[0,1] neg_hi:[0,1]
	v_exp_f32_e32 v76, v76
	v_exp_f32_e32 v77, v77
	v_pk_add_f32 v[80:81], v[80:81], v[196:197] op_sel_hi:[1,0] neg_lo:[0,1] neg_hi:[0,1]
	v_exp_f32_e32 v78, v78
	v_exp_f32_e32 v79, v79
	v_exp_f32_e32 v80, v80
	v_exp_f32_e32 v81, v81
	v_cvt_pk_f16_f32 v214, v66, v67
	v_cvt_pk_f16_f32 v215, v68, v69
	v_cvt_pk_f16_f32 v216, v70, v71
	v_cvt_pk_f16_f32 v217, v72, v73
	v_cvt_pk_f16_f32 v218, v74, v75
	v_cvt_pk_f16_f32 v219, v76, v77
	v_cvt_pk_f16_f32 v220, v78, v79
	v_cvt_pk_f16_f32 v221, v80, v81
	v_pk_add_f32 v[222:223], v[66:67], v[68:69]
	v_pk_add_f32 v[224:225], v[70:71], v[72:73]
	v_pk_add_f32 v[226:227], v[74:75], v[76:77]
	v_pk_add_f32 v[228:229], v[78:79], v[80:81]
	v_pk_add_f32 v[222:223], v[222:223], v[224:225]
	v_pk_add_f32 v[226:227], v[226:227], v[228:229]
	v_pk_add_f32 v[222:223], v[222:223], v[226:227]
	v_add_f32_e32 v222, v222, v223
	v_add_f32_e32 v1, v1, v222
	v_mfma_f32_32x32x16_f16 v[34:49], v[138:141], v[214:217], v[34:49]
	v_mfma_f32_32x32x16_f16 v[50:65], v[146:149], v[214:217], v[50:65]
	v_mfma_f32_32x32x16_f16 v[34:49], v[142:145], v[218:221], v[34:49]
	v_mfma_f32_32x32x16_f16 v[50:65], v[150:153], v[218:221], v[50:65]
	s_branch .Lend_gqa
.Lresc_gqa_0:
	s_nop 11
	v_max_f32_e32 v233, v194, v232
	v_sub_f32_e32 v230, v194, v233
	v_exp_f32_e32 v230, v230
	v_mov_b32_e32 v194, v233
	v_mul_f32_e32 v183, v183, v230
	v_pk_mul_f32 v[2:3], v[2:3], v[230:231] op_sel_hi:[1,0]
	v_pk_mul_f32 v[4:5], v[4:5], v[230:231] op_sel_hi:[1,0]
	v_pk_mul_f32 v[6:7], v[6:7], v[230:231] op_sel_hi:[1,0]
	v_pk_mul_f32 v[8:9], v[8:9], v[230:231] op_sel_hi:[1,0]
	v_pk_mul_f32 v[10:11], v[10:11], v[230:231] op_sel_hi:[1,0]
	v_pk_mul_f32 v[12:13], v[12:13], v[230:231] op_sel_hi:[1,0]
	v_pk_mul_f32 v[14:15], v[14:15], v[230:231] op_sel_hi:[1,0]
	v_pk_mul_f32 v[16:17], v[16:17], v[230:231] op_sel_hi:[1,0]
	v_pk_mul_f32 v[18:19], v[18:19], v[230:231] op_sel_hi:[1,0]
	v_pk_mul_f32 v[20:21], v[20:21], v[230:231] op_sel_hi:[1,0]
	v_pk_mul_f32 v[22:23], v[22:23], v[230:231] op_sel_hi:[1,0]
	v_pk_mul_f32 v[24:25], v[24:25], v[230:231] op_sel_hi:[1,0]
	v_pk_mul_f32 v[26:27], v[26:27], v[230:231] op_sel_hi:[1,0]
	v_pk_mul_f32 v[28:29], v[28:29], v[230:231] op_sel_hi:[1,0]
	v_pk_mul_f32 v[30:31], v[30:31], v[230:231] op_sel_hi:[1,0]
	v_pk_mul_f32 v[32:33], v[32:33], v[230:231] op_sel_hi:[1,0]
	s_branch .Lcont_gqa_0
.Lresc_gqa_1:
	s_nop 11
	v_max_f32_e32 v233, v196, v232
	v_sub_f32_e32 v230, v196, v233
	v_exp_f32_e32 v230, v230
	v_mov_b32_e32 v196, v233
	v_mul_f32_e32 v1, v1, v230
	v_pk_mul_f32 v[34:35], v[34:35], v[230:231] op_sel_hi:[1,0]
	v_pk_mul_f32 v[36:37], v[36:37], v[230:231] op_sel_hi:[1,0]
	v_pk_mul_f32 v[38:39], v[38:39], v[230:231] op_sel_hi:[1,0]
	v_pk_mul_f32 v[40:41], v[40:41], v[230:231] op_sel_hi:[1,0]
	v_pk_mul_f32 v[42:43], v[42:43], v[230:231] op_sel_hi:[1,0]
	v_pk_mul_f32 v[44:45], v[44:45], v[230:231] op_sel_hi:[1,0]
	v_pk_mul_f32 v[46:47], v[46:47], v[230:231] op_sel_hi:[1,0]
	v_pk_mul_f32 v[48:49], v[48:49], v[230:231] op_sel_hi:[1,0]
	v_pk_mul_f32 v[50:51], v[50:51], v[230:231] op_sel_hi:[1,0]
	v_pk_mul_f32 v[52:53], v[52:53], v[230:231] op_sel_hi:[1,0]
	v_pk_mul_f32 v[54:55], v[54:55], v[230:231] op_sel_hi:[1,0]
	v_pk_mul_f32 v[56:57], v[56:57], v[230:231] op_sel_hi:[1,0]
	v_pk_mul_f32 v[58:59], v[58:59], v[230:231] op_sel_hi:[1,0]
	v_pk_mul_f32 v[60:61], v[60:61], v[230:231] op_sel_hi:[1,0]
	v_pk_mul_f32 v[62:63], v[62:63], v[230:231] op_sel_hi:[1,0]
	v_pk_mul_f32 v[64:65], v[64:65], v[230:231] op_sel_hi:[1,0]
	s_branch .Lcont_gqa_1

; template <int DQ, bool NA, int NQG>
; DI void attn_wg(const half_t* Qp, const half_t* Kp, const half_t* Vp, int q0, bool active, int seg0_start, int seg0_tiles,
;                 int seg1_start, int seg1_tiles, const float* rpb_h, int rq, char* smem, int tid, f16v (&O)[2][NQG]) {
;     ...
;     if (more) {
;       char* nb = smem + ((it + 1) & 1) * ATT_STAGE;
;       if (kc0 < KCH) *(uint4*)((half_t*)nb + ks0) = kreg0;
;       if (DQ == 96 && kc1 < KCH) *(uint4*)((half_t*)nb + ks1) = kreg1;
;       *(uint4*)((half_t*)(nb + ATT_VOFF) + vs0) = vreg;
;     }
;     __syncthreads();
.Lend_gqa:
.LBB0_1924:
	s_andn2_b64 vcc, exec, s[8:9]
	s_cbranch_vccnz .LBB0_1928
	s_bitcmp1_b32 s46, 0
	s_cselect_b32 s22, 0x5800, 0
	s_and_saveexec_b64 s[8:9], s[2:3]
	s_cbranch_execz .LBB0_1927
	v_lshl_add_u32 v66, v181, 1, s22
	s_waitcnt vmcnt(1)
	ds_write_b128 v66, v[130:133]

; template <int DQ, bool NA, int NQG>
; DI void attn_wg(const half_t* Qp, const half_t* Kp, const half_t* Vp, int q0, bool active, int seg0_start, int seg0_tiles,
;                 int seg1_start, int seg1_tiles, const float* rpb_h, int rq, char* smem, int tid, f16v (&O)[2][NQG]) {
;     ...
;   const int r0w = min(max(rq - 4, 0), 24);
;   {
;     const int k0 = (0 < seg0_tiles) ? seg0_start : seg1_start;
;     if (kc0 < KCH) kreg0 = *(const uint4*)(kg0 + (size_t)k0 * DQ);
;     if (DQ == 96 && kc1 < KCH) kreg1 = *(const uint4*)(kg1 + (size_t)k0 * DQ);
;     vreg = *(const uint4*)(vg + k0);
;     if (kc0 < KCH) *(uint4*)((half_t*)smem + ks0) = kreg0;
;     if (DQ == 96 && kc1 < KCH) *(uint4*)((half_t*)smem + ks1) = kreg1;
;     *(uint4*)((half_t*)(smem + ATT_VOFF) + vs0) = vreg;
;   }
;   __syncthreads();
;   for (int it = 0; it < ntiles; ++it) {
; DI void phase_attn(int l, half_t* big, bool need_ctx, char* smem, int wv_) {
;     ...
;         attn_wg<64, true, 2>(big + B_QNA + (size_t)(b * 4 + hh) * TOK * 64, big + B_KNA + (size_t)(b * 4 + hh) * TOK * 64,
;                              big + B_VTNA + (size_t)(b * 4 + hh) * 64 * TOK, q0, active, seg0s, seg0n, SEQ, 4,
;                              p->na_rpb + (size_t)(l * 4 + hh) * 15 * 31, rq, smem, tid_m, O);
.LBB0_2086:
	s_or_b64 exec, exec, s[22:23]
	s_waitcnt lgkmcnt(0)
	s_add_i32 s40, s53, s31
	s_mulk_i32 s40, 0x744
	s_add_u32 s74, s8, s40
	s_addc_u32 s75, s9, 0
	v_mbcnt_lo_u32_b32 v1, -1, 0
	v_mbcnt_hi_u32_b32 v1, -1, v1
	v_or_b32_e32 v1, s55, v1
	v_cmp_gt_u32_e32 vcc, 0x1d1, v1
	s_and_saveexec_b64 s[78:79], vcc
	v_lshlrev_b32_e32 v1, 2, v1
	global_load_dword v2, v1, s[74:75]
	v_add_u32_e32 v1, 0x1c000, v1
	s_waitcnt vmcnt(0)
	ds_write_b32 v1, v2
	s_or_b64 exec, exec, s[78:79]
	s_cmp_lt_i32 s60, -3
	s_waitcnt vmcnt(0)
	ds_write_b128 v185, v[148:151] offset:13312
	s_waitcnt lgkmcnt(0)
	s_barrier
	s_cbranch_scc1 .LBB0_2173
	s_add_i32 s22, s53, s31
	s_ashr_i32 s56, s24, 6
	s_mul_hi_i32 s23, s22, 0x744
	s_mulk_i32 s22, 0x744
	s_add_u32 s22, s8, s22
	s_addc_u32 s23, s9, s23
	s_max_i32 s8, s56, 4
	s_add_i32 s8, s8, -4
	v_mov_b32_e32 v14, v0
	v_mov_b32_e32 v15, v0
	s_min_u32 s66, s8, 24
	v_mov_b32_e32 v1, v0
	v_mov_b32_e32 v2, v0
	v_mov_b32_e32 v3, v0
	v_mov_b32_e32 v4, v0
	v_mov_b32_e32 v5, v0
	v_mov_b32_e32 v6, v0
	v_mov_b32_e32 v7, v0
	v_mov_b32_e32 v8, v0
	v_mov_b32_e32 v9, v0
	v_mov_b32_e32 v10, v0
	v_mov_b32_e32 v11, v0
	v_mov_b32_e32 v12, v0
	v_mov_b32_e32 v13, v0
	v_mov_b64_e32 v[78:79], v[14:15]
	v_mov_b64_e32 v[46:47], v[14:15]
	v_mov_b64_e32 v[62:63], v[14:15]
	v_mov_b64_e32 v[30:31], v[14:15]
	s_add_i32 s61, s60, 4
	s_add_i32 s68, s66, 8
	s_mov_b32 s28, 0
	v_mov_b32_e32 v158, 0xf149f2ca
	v_mov_b32_e32 v153, 0
	v_mov_b64_e32 v[76:77], v[12:13]
	v_mov_b64_e32 v[74:75], v[10:11]
	v_mov_b64_e32 v[72:73], v[8:9]
	v_mov_b64_e32 v[70:71], v[6:7]
	v_mov_b64_e32 v[68:69], v[4:5]
	v_mov_b64_e32 v[66:67], v[2:3]
	v_mov_b64_e32 v[64:65], v[0:1]
	v_mov_b64_e32 v[44:45], v[12:13]
	v_mov_b64_e32 v[42:43], v[10:11]
	v_mov_b64_e32 v[40:41], v[8:9]
	v_mov_b64_e32 v[38:39], v[6:7]
	v_mov_b64_e32 v[36:37], v[4:5]
	v_mov_b64_e32 v[34:35], v[2:3]
	v_mov_b64_e32 v[32:33], v[0:1]
	v_mov_b64_e32 v[60:61], v[12:13]
	v_mov_b64_e32 v[58:59], v[10:11]
	v_mov_b64_e32 v[56:57], v[8:9]
	v_mov_b64_e32 v[54:55], v[6:7]
	v_mov_b64_e32 v[52:53], v[4:5]
	v_mov_b64_e32 v[50:51], v[2:3]
	v_mov_b64_e32 v[48:49], v[0:1]
	v_mov_b64_e32 v[28:29], v[12:13]
	v_mov_b64_e32 v[26:27], v[10:11]
	v_mov_b64_e32 v[24:25], v[8:9]
	v_mov_b64_e32 v[22:23], v[6:7]
	v_mov_b64_e32 v[20:21], v[4:5]
	v_mov_b64_e32 v[18:19], v[2:3]
	v_mov_b64_e32 v[16:17], v[0:1]
	v_mov_b32_e32 v159, 0
	v_mov_b32_e32 v14, 0xf149f2ca

; template <int DQ, bool NA, int NQG>
; DI void attn_wg(const half_t* Qp, const half_t* Kp, const half_t* Vp, int q0, bool active, int seg0_start, int seg0_tiles,
;                 int seg1_start, int seg1_tiles, const float* rpb_h, int rq, char* smem, int tid, f16v (&O)[2][NQG]) {
;     ...
;         for (int ks = 0; ks < NKS; ++ks) {
;           const h8 kf = *(const h8*)(ksm + (st * 32) * KSTR + ks * 16);
; #pragma unroll
;           for (int qg = 0; qg < NQG; ++qg) S[qg] = __builtin_amdgcn_mfma_f32_32x32x16_f16(kf, qf[qg][ks], S[qg], 0, 0, 0);
;         }
;         if (masked) {
;           const int cb = st * 32;
;           const int dr = krow - rq + 7;
; #pragma unroll
;           for (int qg = 0; qg < NQG; ++qg) {
;             const int qc = qg * 32 + r;
;             const int cs = min(max(qc - 8, 0), 48);
; #pragma unroll
;             for (int i = 0; i < 16; ++i) {
;               const int c = cb + (i & 3) + 8 * (i >> 2) + 4 * h;
;               const bool valid = (c >= cs) && (c < cs + 16);
;               float bias = 0.f;
;               if (valid) bias = rpb_h[dr * 31 + (c - qc + 15)] * LOG2E;
;               S[qg][i] = valid ? S[qg][i] + bias : -1e30f;
;             }
;           }
;         }
.LBB0_2095:
	s_mul_i32 s8, s46, 0x1200
	v_add_u32_e32 v6, s8, v1
	ds_read_b128 v[2:5], v6
	s_andn2_b64 vcc, exec, s[26:27]
	s_waitcnt lgkmcnt(0)
	v_mfma_f32_32x32x16_f16 v[96:111], v[2:5], v[112:115], 0
	v_mfma_f32_32x32x16_f16 v[80:95], v[2:5], v[128:131], 0
	ds_read_b128 v[2:5], v6 offset:32
	s_waitcnt lgkmcnt(0)
	v_mfma_f32_32x32x16_f16 v[96:111], v[2:5], v[116:119], v[96:111]
	v_mfma_f32_32x32x16_f16 v[80:95], v[2:5], v[132:135], v[80:95]
	ds_read_b128 v[2:5], v6 offset:64
	s_waitcnt lgkmcnt(0)
	v_mfma_f32_32x32x16_f16 v[96:111], v[2:5], v[120:123], v[96:111]
	v_mfma_f32_32x32x16_f16 v[80:95], v[2:5], v[136:139], v[80:95]
	ds_read_b128 v[2:5], v6 offset:96
	s_waitcnt lgkmcnt(0)
	v_mfma_f32_32x32x16_f16 v[96:111], v[2:5], v[124:127], v[96:111]
	v_mfma_f32_32x32x16_f16 v[80:95], v[2:5], v[140:143], v[80:95]
	s_cbranch_vccnz .LBB0_2161
	s_lshl_b32 s40, s46, 7
	v_add_u32_e32 v2, v160, v181
	v_add_u32_e32 v3, v162, v181
	v_lshl_add_u32 v2, v2, 2, s40
	v_lshl_add_u32 v3, v3, 2, s40
	v_add_u32_e32 v2, 0x1c000, v2
	v_add_u32_e32 v3, 0x1c000, v3
	ds_read2_b32 v[168:169], v2 offset0:0 offset1:1
	ds_read2_b32 v[170:171], v2 offset0:2 offset1:3
	ds_read2_b32 v[206:207], v2 offset0:8 offset1:9
	ds_read2_b32 v[210:211], v2 offset0:10 offset1:11
	ds_read2_b32 v[212:213], v2 offset0:16 offset1:17
	ds_read2_b32 v[218:219], v2 offset0:18 offset1:19
	ds_read2_b32 v[222:223], v2 offset0:24 offset1:25
	ds_read2_b32 v[226:227], v2 offset0:26 offset1:27
	ds_read2_b32 v[172:173], v3 offset0:0 offset1:1
	ds_read2_b32 v[204:205], v3 offset0:2 offset1:3
	ds_read2_b32 v[208:209], v3 offset0:8 offset1:9
	ds_read2_b32 v[214:215], v3 offset0:10 offset1:11
	ds_read2_b32 v[216:217], v3 offset0:16 offset1:17
	ds_read2_b32 v[220:221], v3 offset0:18 offset1:19
	ds_read2_b32 v[224:225], v3 offset0:24 offset1:25
	ds_read2_b32 v[228:229], v3 offset0:26 offset1:27
	v_lshl_or_b32 v11, s46, 5, v181
	v_sub_u32_e32 v4, v11, v233
	v_sub_u32_e32 v5, v11, v236
	v_mov_b32_e32 v10, 0xf149f2ca
	s_waitcnt lgkmcnt(0)
	v_add_u32_e32 v6, 0, v4
	v_add_u32_e32 v7, 1, v4
	v_add_u32_e32 v8, 2, v4
	v_add_u32_e32 v9, 3, v4
	v_cmp_gt_u32_e32 vcc, 16, v6
	v_cmp_gt_u32_e64 s[8:9], 16, v7
	v_cmp_gt_u32_e64 s[74:75], 16, v8
	v_cmp_gt_u32_e64 s[78:79], 16, v9
	v_fmamk_f32 v168, v168, 0x3fb8aa3b, v96
	v_fmamk_f32 v169, v169, 0x3fb8aa3b, v97
	v_fmamk_f32 v170, v170, 0x3fb8aa3b, v98
	v_fmamk_f32 v171, v171, 0x3fb8aa3b, v99
	v_cndmask_b32_e32 v168, v10, v168, vcc
	v_cndmask_b32_e64 v169, v10, v169, s[8:9]
	v_cndmask_b32_e64 v170, v10, v170, s[74:75]
	v_cndmask_b32_e64 v171, v10, v171, s[78:79]
	v_add_u32_e32 v6, 8, v4
	v_add_u32_e32 v7, 9, v4
	v_add_u32_e32 v8, 10, v4
	v_add_u32_e32 v9, 11, v4
	v_cmp_gt_u32_e32 vcc, 16, v6
	v_cmp_gt_u32_e64 s[8:9], 16, v7
	v_cmp_gt_u32_e64 s[74:75], 16, v8
	v_cmp_gt_u32_e64 s[78:79], 16, v9
	v_fmamk_f32 v206, v206, 0x3fb8aa3b, v100
	v_fmamk_f32 v207, v207, 0x3fb8aa3b, v101
	v_fmamk_f32 v210, v210, 0x3fb8aa3b, v102
	v_fmamk_f32 v211, v211, 0x3fb8aa3b, v103
	v_cndmask_b32_e32 v206, v10, v206, vcc
	v_cndmask_b32_e64 v207, v10, v207, s[8:9]
	v_cndmask_b32_e64 v210, v10, v210, s[74:75]
	v_cndmask_b32_e64 v211, v10, v211, s[78:79]
	v_add_u32_e32 v6, 16, v4
	v_add_u32_e32 v7, 17, v4
	v_add_u32_e32 v8, 18, v4
	v_add_u32_e32 v9, 19, v4
	v_cmp_gt_u32_e32 vcc, 16, v6
	v_cmp_gt_u32_e64 s[8:9], 16, v7
	v_cmp_gt_u32_e64 s[74:75], 16, v8
	v_cmp_gt_u32_e64 s[78:79], 16, v9
	v_fmamk_f32 v212, v212, 0x3fb8aa3b, v104
	v_fmamk_f32 v213, v213, 0x3fb8aa3b, v105
	v_fmamk_f32 v218, v218, 0x3fb8aa3b, v106
	v_fmamk_f32 v219, v219, 0x3fb8aa3b, v107
	v_cndmask_b32_e32 v212, v10, v212, vcc
	v_cndmask_b32_e64 v213, v10, v213, s[8:9]
	v_cndmask_b32_e64 v218, v10, v218, s[74:75]
	v_cndmask_b32_e64 v219, v10, v219, s[78:79]
	v_add_u32_e32 v6, 24, v4
	v_add_u32_e32 v7, 25, v4
	v_add_u32_e32 v8, 26, v4
	v_add_u32_e32 v9, 27, v4
	v_cmp_gt_u32_e32 vcc, 16, v6
	v_cmp_gt_u32_e64 s[8:9], 16, v7
	v_cmp_gt_u32_e64 s[74:75], 16, v8
	v_cmp_gt_u32_e64 s[78:79], 16, v9
	v_fmamk_f32 v222, v222, 0x3fb8aa3b, v108
	v_fmamk_f32 v223, v223, 0x3fb8aa3b, v109
	v_fmamk_f32 v226, v226, 0x3fb8aa3b, v110
	v_fmamk_f32 v227, v227, 0x3fb8aa3b, v111
	v_cndmask_b32_e32 v222, v10, v222, vcc
	v_cndmask_b32_e64 v223, v10, v223, s[8:9]
	v_cndmask_b32_e64 v226, v10, v226, s[74:75]
	v_cndmask_b32_e64 v227, v10, v227, s[78:79]
	v_add_u32_e32 v6, 0, v5
	v_add_u32_e32 v7, 1, v5
	v_add_u32_e32 v8, 2, v5
	v_add_u32_e32 v9, 3, v5
	v_cmp_gt_u32_e32 vcc, 16, v6
	v_cmp_gt_u32_e64 s[8:9], 16, v7
	v_cmp_gt_u32_e64 s[74:75], 16, v8
	v_cmp_gt_u32_e64 s[78:79], 16, v9
	v_fmamk_f32 v172, v172, 0x3fb8aa3b, v80
	v_fmamk_f32 v173, v173, 0x3fb8aa3b, v81
	v_fmamk_f32 v204, v204, 0x3fb8aa3b, v82
	v_fmamk_f32 v205, v205, 0x3fb8aa3b, v83
	v_cndmask_b32_e32 v172, v10, v172, vcc
	v_cndmask_b32_e64 v173, v10, v173, s[8:9]
	v_cndmask_b32_e64 v204, v10, v204, s[74:75]
	v_cndmask_b32_e64 v205, v10, v205, s[78:79]
	v_add_u32_e32 v6, 8, v5
	v_add_u32_e32 v7, 9, v5
	v_add_u32_e32 v8, 10, v5
	v_add_u32_e32 v9, 11, v5
	v_cmp_gt_u32_e32 vcc, 16, v6
	v_cmp_gt_u32_e64 s[8:9], 16, v7
	v_cmp_gt_u32_e64 s[74:75], 16, v8
	v_cmp_gt_u32_e64 s[78:79], 16, v9
	v_fmamk_f32 v208, v208, 0x3fb8aa3b, v84
	v_fmamk_f32 v209, v209, 0x3fb8aa3b, v85
	v_fmamk_f32 v214, v214, 0x3fb8aa3b, v86
	v_fmamk_f32 v215, v215, 0x3fb8aa3b, v87
	v_cndmask_b32_e32 v208, v10, v208, vcc
	v_cndmask_b32_e64 v209, v10, v209, s[8:9]
	v_cndmask_b32_e64 v214, v10, v214, s[74:75]
	v_cndmask_b32_e64 v215, v10, v215, s[78:79]
	v_add_u32_e32 v6, 16, v5
	v_add_u32_e32 v7, 17, v5
	v_add_u32_e32 v8, 18, v5
	v_add_u32_e32 v9, 19, v5
	v_cmp_gt_u32_e32 vcc, 16, v6
	v_cmp_gt_u32_e64 s[8:9], 16, v7
	v_cmp_gt_u32_e64 s[74:75], 16, v8
	v_cmp_gt_u32_e64 s[78:79], 16, v9
	v_fmamk_f32 v216, v216, 0x3fb8aa3b, v88
	v_fmamk_f32 v217, v217, 0x3fb8aa3b, v89
	v_fmamk_f32 v220, v220, 0x3fb8aa3b, v90
	v_fmamk_f32 v221, v221, 0x3fb8aa3b, v91
	v_cndmask_b32_e32 v216, v10, v216, vcc
	v_cndmask_b32_e64 v217, v10, v217, s[8:9]
	v_cndmask_b32_e64 v220, v10, v220, s[74:75]
	v_cndmask_b32_e64 v221, v10, v221, s[78:79]
	v_add_u32_e32 v6, 24, v5
	v_add_u32_e32 v7, 25, v5
	v_add_u32_e32 v8, 26, v5
	v_add_u32_e32 v9, 27, v5
	v_cmp_gt_u32_e32 vcc, 16, v6
	v_cmp_gt_u32_e64 s[8:9], 16, v7
	v_cmp_gt_u32_e64 s[74:75], 16, v8
	v_cmp_gt_u32_e64 s[78:79], 16, v9
	v_fmamk_f32 v224, v224, 0x3fb8aa3b, v92
	v_fmamk_f32 v225, v225, 0x3fb8aa3b, v93
	v_fmamk_f32 v228, v228, 0x3fb8aa3b, v94
	v_fmamk_f32 v229, v229, 0x3fb8aa3b, v95
	v_cndmask_b32_e32 v224, v10, v224, vcc
	v_cndmask_b32_e64 v225, v10, v225, s[8:9]
	v_cndmask_b32_e64 v228, v10, v228, s[74:75]
	v_cndmask_b32_e64 v229, v10, v229, s[78:79]
	s_branch .LBB0_2162
